# attnqk: attention QK^T chunk loop rotates the first-half K fragments through 8 register quads with 6 blocks of LDS reads in flight (counted lgkmcnt) instead of read-wait-MFMA per block
# baseline (speedup 1.0000x reference)
.LBB0_1104:
	v_add_u32_e32 v88, v122, v120
	ds_read_b128 v[142:145], v121
	ds_read_b128 v[150:153], v121 offset:64
	ds_read_b128 v[146:149], v88 offset:18432
	ds_read_b128 v[154:157], v88 offset:18496
	ds_read_b128 v[220:223], v88 offset:20736
	ds_read_b128 v[158:161], v88 offset:20800
	ds_read_b128 v[224:227], v88 offset:23040
	ds_read_b128 v[162:165], v88 offset:23104
	ds_read_b128 v[228:231], v88 offset:25344
	ds_read_b128 v[166:169], v88 offset:25408
	ds_read_b128 v[236:239], v88 offset:27648
	ds_read_b128 v[172:175], v88 offset:27712
	ds_read_b128 v[240:243], v88 offset:29952
	ds_read_b128 v[176:179], v88 offset:30016
	s_waitcnt lgkmcnt(11)
	v_mfma_f32_16x16x32_bf16 v[60:63], v[142:145], v[146:149], v[60:63]
	ds_read_b128 v[244:247], v88 offset:32256
	ds_read_b128 v[180:183], v88 offset:32320
	s_waitcnt lgkmcnt(11)
	v_mfma_f32_16x16x32_bf16 v[56:59], v[142:145], v[220:223], v[56:59]
	ds_read_b128 v[248:251], v88 offset:34560
	ds_read_b128 v[184:187], v88 offset:34624
	s_waitcnt lgkmcnt(11)
	v_mfma_f32_16x16x32_bf16 v[52:55], v[142:145], v[224:227], v[52:55]
	ds_read_b128 v[146:149], v88 offset:36864
	ds_read_b128 v[188:191], v88 offset:36928
	s_waitcnt lgkmcnt(11)
	v_mfma_f32_16x16x32_bf16 v[48:51], v[142:145], v[228:231], v[48:51]
	ds_read_b128 v[220:223], v88 offset:39168
	ds_read_b128 v[192:195], v88 offset:39232
	s_waitcnt lgkmcnt(11)
	v_mfma_f32_16x16x32_bf16 v[44:47], v[142:145], v[236:239], v[44:47]
	ds_read_b128 v[224:227], v88 offset:41472
	ds_read_b128 v[196:199], v88 offset:41536
	s_waitcnt lgkmcnt(11)
	v_mfma_f32_16x16x32_bf16 v[40:43], v[142:145], v[240:243], v[40:43]
	ds_read_b128 v[228:231], v88 offset:43776
	ds_read_b128 v[200:203], v88 offset:43840
	s_waitcnt lgkmcnt(11)
	v_mfma_f32_16x16x32_bf16 v[36:39], v[142:145], v[244:247], v[36:39]
	ds_read_b128 v[236:239], v88 offset:46080
	ds_read_b128 v[204:207], v88 offset:46144
	s_waitcnt lgkmcnt(11)
	v_mfma_f32_16x16x32_bf16 v[32:35], v[142:145], v[248:251], v[32:35]
	ds_read_b128 v[240:243], v88 offset:48384
	ds_read_b128 v[208:211], v88 offset:48448
	s_waitcnt lgkmcnt(11)
	v_mfma_f32_16x16x32_bf16 v[28:31], v[142:145], v[146:149], v[28:31]
	ds_read_b128 v[244:247], v88 offset:50688
	ds_read_b128 v[212:215], v88 offset:50752
	s_waitcnt lgkmcnt(11)
	v_mfma_f32_16x16x32_bf16 v[24:27], v[142:145], v[220:223], v[24:27]
	ds_read_b128 v[248:251], v88 offset:52992
	ds_read_b128 v[216:219], v88 offset:53056
	s_waitcnt lgkmcnt(11)
	v_mfma_f32_16x16x32_bf16 v[16:19], v[142:145], v[224:227], v[16:19]
	s_waitcnt lgkmcnt(9)
	v_mfma_f32_16x16x32_bf16 v[12:15], v[142:145], v[228:231], v[12:15]
	s_waitcnt lgkmcnt(7)
	v_mfma_f32_16x16x32_bf16 v[8:11], v[142:145], v[236:239], v[8:11]
	s_waitcnt lgkmcnt(5)
	v_mfma_f32_16x16x32_bf16 v[4:7], v[142:145], v[240:243], v[4:7]
	s_waitcnt lgkmcnt(3)
	v_mfma_f32_16x16x32_bf16 v[0:3], v[142:145], v[244:247], v[0:3]
	s_add_u32 s10, s10, 0x80
	s_addc_u32 s11, s11, 0
	s_cmpk_eq_i32 s10, 0x400
	s_waitcnt lgkmcnt(0)
	s_barrier
	v_mfma_f32_16x16x32_bf16 v[20:23], v[142:145], v[248:251], v[20:23]
	v_mfma_f32_16x16x32_bf16 v[60:63], v[150:153], v[154:157], v[60:63]
	v_mfma_f32_16x16x32_bf16 v[56:59], v[150:153], v[158:161], v[56:59]
	v_mfma_f32_16x16x32_bf16 v[52:55], v[150:153], v[162:165], v[52:55]
	v_mfma_f32_16x16x32_bf16 v[48:51], v[150:153], v[166:169], v[48:51]
	v_mfma_f32_16x16x32_bf16 v[44:47], v[150:153], v[172:175], v[44:47]
	v_mfma_f32_16x16x32_bf16 v[40:43], v[150:153], v[176:179], v[40:43]
	v_mfma_f32_16x16x32_bf16 v[36:39], v[150:153], v[180:183], v[36:39]
	v_mfma_f32_16x16x32_bf16 v[32:35], v[150:153], v[184:187], v[32:35]
	v_mfma_f32_16x16x32_bf16 v[28:31], v[150:153], v[188:191], v[28:31]
	v_mfma_f32_16x16x32_bf16 v[24:27], v[150:153], v[192:195], v[24:27]
	v_mfma_f32_16x16x32_bf16 v[16:19], v[150:153], v[196:199], v[16:19]
	v_mfma_f32_16x16x32_bf16 v[12:15], v[150:153], v[200:203], v[12:15]
	v_mfma_f32_16x16x32_bf16 v[8:11], v[150:153], v[204:207], v[8:11]
	v_mfma_f32_16x16x32_bf16 v[4:7], v[150:153], v[208:211], v[4:7]
	v_mfma_f32_16x16x32_bf16 v[0:3], v[150:153], v[212:215], v[0:3]
	v_mfma_f32_16x16x32_bf16 v[20:23], v[150:153], v[216:219], v[20:23]
	s_cbranch_scc1 .LBB0_1107
